# EL phase: one activation path per element (tanh as 2*sigmoid(2x)-1 with per-lane constants, identity by select) instead of two exec-masked branches
# baseline (speedup 1.0000x reference)
; #define KAS __attribute__((address_space(4)))
; __device__ __forceinline__ void el_phase(const KAS Args& a, int i, const int tid_, const int bid, const int nblk) {
;     const bf16_t* Z = (const bf16_t*)(a.ws + WS_HZ); bf16_t* LA = (bf16_t*)((unsigned char*)a.out + OUT_LA);
;     const float* mu = a.mu + i * 1792 + 1536;
;     const int gt = bid * 512 + tid_, NGT = nblk * 512;
;     for (int ib = gt; ib < M * 32; ib += 4 * NGT) { u32x4 rc[4], rp[4];
; #pragma unroll
;         for (int k = 0; k < 4; ++k) { const int idx = ib + k * NGT; const int ii = idx < M * 32 ? idx : ib; const int m = ii >> 5, c0 = (ii & 31) * 8, t = m & (T - 1);
;             rc[k] = *(const u32x4*)(Z + (size_t)m * ZC + 1536 + c0); rp[k] = (t > 0) ? *(const u32x4*)(Z + (size_t)(m - 1) * ZC + 1536 + c0) : (u32x4){0u, 0u, 0u, 0u}; }
; #pragma unroll
;         for (int k = 0; k < 4; ++k) { const int idx = ib + k * NGT; if (idx >= M * 32) break; const int m = idx >> 5, c0 = (idx & 31) * 8;
.LBB0_196:
	s_andn2_b64 vcc, exec, s[2:3]
	s_cbranch_vccnz .LBB0_496
	v_readlane_b32 s2, v255, 21
	s_cmp_lt_i32 s2, 4
	s_cbranch_scc1 .LBB0_201
	s_cmp_lt_i32 s2, 5
	s_mov_b64 s[2:3], -1
	s_mov_b32 s27, 0x200000
	s_mov_b32 s28, 0x1fffff
	s_cbranch_scc0 .LBB0_344
	s_waitcnt vmcnt(8)
	v_lshl_add_u32 v5, s91, 9, v186
	v_cmp_gt_i32_e32 vcc, s27, v5
	s_and_saveexec_b64 s[14:15], vcc
	s_cbranch_execz .LBB0_343
	s_load_dwordx2 s[2:3], s[84:85], 0x118
	s_load_dwordx2 s[6:7], s[84:85], 0x60
	s_mul_i32 s92, s83, 0x700
	v_lshlrev_b32_e32 v0, 3, v186
	v_lshl_add_u32 v38, s91, 12, v0
	s_waitcnt lgkmcnt(0)
	s_add_u32 s16, s2, 0x8000000
	s_addc_u32 s17, s3, 0
	s_lshl_b64 s[2:3], s[92:93], 2
	s_add_u32 s2, s6, s2
	s_addc_u32 s3, s7, s3
	s_add_u32 s18, s2, 0x1800
	s_addc_u32 s19, s3, 0
	s_lshl_b32 s24, s90, 9
	s_lshl_b32 s25, s90, 10
	s_lshl_b32 s26, s90, 14
	s_mov_b64 s[20:21], 0
	v_and_b32_e32 v78, 0xf8, v38
	v_cmp_gt_u32_e32 vcc, 64, v78
	v_mov_b32_e32 v57, 0xbfb8aa3b
	v_mov_b32_e32 v58, 0xc038aa3b
	v_cndmask_b32_e32 v54, v57, v58, vcc
	v_cndmask_b32_e64 v55, 1.0, 2.0, vcc
	v_cndmask_b32_e64 v56, 0, -1.0, vcc
	v_lshlrev_b32_e32 v78, 2, v78
	global_load_dwordx4 v[46:49], v78, s[18:19]
	global_load_dwordx4 v[50:53], v78, s[18:19] offset:16
	s_waitcnt vmcnt(0)
	s_branch .LBB0_204

; __device__ __forceinline__ float fast_sigmoid(float x) { return __builtin_amdgcn_rcpf(1.0f + __builtin_amdgcn_exp2f(-1.4426950408889634f * x)); }
; __device__ __forceinline__ void unpack8(const u32x4 w, float (&f)[8]) { f[0] = bflo(w.x); f[1] = bfhi(w.x); f[2] = bflo(w.y); f[3] = bfhi(w.y); f[4] = bflo(w.z); f[5] = bfhi(w.z); f[6] = bflo(w.w); f[7] = bfhi(w.w); }
; __device__ __forceinline__ u32x4 pack8(const float (&f)[8]) { return (u32x4){pk2(f[0], f[1]), pk2(f[2], f[3]), pk2(f[4], f[5]), pk2(f[6], f[7])}; }
; __device__ __forceinline__ void el_phase(const KAS Args& a, int i, const int tid_, const int bid, const int nblk) {
;     ...
;         for (int k = 0; k < 4; ++k) { const int idx = ib + k * NGT; if (idx >= M * 32) break; const int m = idx >> 5, c0 = (idx & 31) * 8;
;             float zc[8], zp[8], o[8]; unpack8(rc[k], zc); unpack8(rp[k], zp);
; #pragma unroll
;             for (int e = 0; e < 8; ++e) { const float z = zc[e] + (zp[e] - zc[e]) * mu[c0 + e];
;                 o[e] = (c0 < 64) ? (2.0f * fast_sigmoid(2.0f * z) - 1.0f) : (c0 < 128 ? z : fast_sigmoid(z)); }
;             *(u32x4*)(LA + (size_t)m * LAC + c0) = pack8(o); } }
.LBB0_202:
	v_ashrrev_i32_e32 v0, 5, v40
	v_cvt_pk_bf16_f32 v7, v10, v1
	v_ashrrev_i32_e32 v1, 31, v0
	v_lshlrev_b64 v[0:1], 9, v[0:1]
	v_cvt_pk_bf16_f32 v4, v2, v4
	v_cvt_pk_bf16_f32 v5, v8, v5
	v_cvt_pk_bf16_f32 v6, v9, v6
	v_lshl_add_u64 v[0:1], v[28:29], 0, v[0:1]
	global_store_dwordx4 v[0:1], v[4:7], off

; __device__ __forceinline__ float fast_sigmoid(float x) { return __builtin_amdgcn_rcpf(1.0f + __builtin_amdgcn_exp2f(-1.4426950408889634f * x)); }
; __device__ __forceinline__ void unpack8(const u32x4 w, float (&f)[8]) { f[0] = bflo(w.x); f[1] = bfhi(w.x); f[2] = bflo(w.y); f[3] = bfhi(w.y); f[4] = bflo(w.z); f[5] = bfhi(w.z); f[6] = bflo(w.w); f[7] = bfhi(w.w); }
; __device__ __forceinline__ u32x4 pack8(const float (&f)[8]) { return (u32x4){pk2(f[0], f[1]), pk2(f[2], f[3]), pk2(f[4], f[5]), pk2(f[6], f[7])}; }
; __device__ __forceinline__ void el_phase(const KAS Args& a, int i, const int tid_, const int bid, const int nblk) {
;     ...
;         for (int k = 0; k < 4; ++k) { const int idx = ib + k * NGT; if (idx >= M * 32) break; const int m = idx >> 5, c0 = (idx & 31) * 8;
;             float zc[8], zp[8], o[8]; unpack8(rc[k], zc); unpack8(rp[k], zp);
; #pragma unroll
;             for (int e = 0; e < 8; ++e) { const float z = zc[e] + (zp[e] - zc[e]) * mu[c0 + e];
;                 o[e] = (c0 < 64) ? (2.0f * fast_sigmoid(2.0f * z) - 1.0f) : (c0 < 128 ? z : fast_sigmoid(z)); }
;             *(u32x4*)(LA + (size_t)m * LAC + c0) = pack8(o); } }
.LBB0_212:
	s_or_b64 exec, exec, s[2:3]
	s_waitcnt vmcnt(0)
	v_lshlrev_b32_e32 v1, 16, v28
	v_lshlrev_b32_e32 v0, 16, v32
	s_movk_i32 s2, 0x80
	v_sub_f32_e32 v43, v0, v1
	v_lshlrev_b32_e32 v0, 2, v42
	v_cmp_lt_u32_e64 s[6:7], 63, v42
	v_cmp_gt_u32_e32 vcc, s2, v42
	s_and_b64 s[6:7], s[6:7], vcc
	v_mov_b32_e32 v42, v46
	v_fmac_f32_e32 v1, v43, v42
	v_mul_f32_e32 v42, v54, v1
	v_exp_f32_e32 v42, v42
	s_nop 0
	v_add_f32_e32 v42, 1.0, v42
	v_rcp_f32_e32 v42, v42
	s_nop 0
	v_fma_f32 v42, v42, v55, v56
	v_cndmask_b32_e64 v42, v42, v1, s[6:7]
	v_mov_b32_e32 v1, v3
	v_lshl_add_u64 v[0:1], s[18:19], 0, v[0:1]
	v_mov_b32_e32 v43, v47
	v_and_b32_e32 v28, 0xffff0000, v28
	v_and_b32_e32 v32, 0xffff0000, v32
	v_sub_f32_e32 v32, v32, v28
	v_fmac_f32_e32 v28, v32, v43
	v_mul_f32_e32 v32, v54, v28
	v_exp_f32_e32 v32, v32
	s_nop 0
	v_add_f32_e32 v32, 1.0, v32
	v_rcp_f32_e32 v32, v32
	s_nop 0
	v_fma_f32 v32, v32, v55, v56
	v_cndmask_b32_e64 v32, v32, v28, s[6:7]
	v_mov_b32_e32 v44, v48
	v_lshlrev_b32_e32 v28, 16, v29
	v_lshlrev_b32_e32 v43, 16, v33
	v_sub_f32_e32 v43, v43, v28
	v_fmac_f32_e32 v28, v43, v44
	v_mul_f32_e32 v43, v54, v28
	v_exp_f32_e32 v43, v43
	s_nop 0
	v_add_f32_e32 v43, 1.0, v43
	v_rcp_f32_e32 v43, v43
	s_nop 0
	v_fma_f32 v43, v43, v55, v56
	v_cndmask_b32_e64 v43, v43, v28, s[6:7]
	v_and_b32_e32 v28, 0xffff0000, v29
	v_and_b32_e32 v29, 0xffff0000, v33
	v_mov_b32_e32 v33, v49
	v_sub_f32_e32 v29, v29, v28
	v_fmac_f32_e32 v28, v29, v33
	v_mul_f32_e32 v33, v54, v28
	v_exp_f32_e32 v33, v33
	s_nop 0
	v_add_f32_e32 v33, 1.0, v33
	v_rcp_f32_e32 v33, v33
	s_nop 0
	v_fma_f32 v33, v33, v55, v56
	v_cndmask_b32_e64 v33, v33, v28, s[6:7]
	v_mov_b32_e32 v44, v50
	v_lshlrev_b32_e32 v28, 16, v30
	v_lshlrev_b32_e32 v29, 16, v34
	v_sub_f32_e32 v29, v29, v28
	v_fmac_f32_e32 v28, v29, v44
	v_mul_f32_e32 v44, v54, v28
	v_exp_f32_e32 v44, v44
	s_nop 0
	v_add_f32_e32 v44, 1.0, v44
	v_rcp_f32_e32 v44, v44
	s_nop 0
	v_fma_f32 v44, v44, v55, v56
	v_cndmask_b32_e64 v44, v44, v28, s[6:7]
	v_and_b32_e32 v28, 0xffff0000, v30
	v_mov_b32_e32 v30, v51
	v_and_b32_e32 v29, 0xffff0000, v34
	v_sub_f32_e32 v29, v29, v28
	v_fmac_f32_e32 v28, v29, v30
	v_mul_f32_e32 v30, v54, v28
	v_exp_f32_e32 v30, v30
	s_nop 0
	v_add_f32_e32 v30, 1.0, v30
	v_rcp_f32_e32 v30, v30
	s_nop 0
	v_fma_f32 v30, v30, v55, v56
	v_cndmask_b32_e64 v30, v30, v28, s[6:7]
	v_mov_b32_e32 v34, v52
	v_lshlrev_b32_e32 v28, 16, v31
	v_lshlrev_b32_e32 v29, 16, v35
	v_sub_f32_e32 v29, v29, v28
	v_fmac_f32_e32 v28, v29, v34
	v_mul_f32_e32 v34, v54, v28
	v_exp_f32_e32 v34, v34
	s_nop 0
	v_add_f32_e32 v34, 1.0, v34
	v_rcp_f32_e32 v34, v34
	s_nop 0
	v_fma_f32 v34, v34, v55, v56
	v_cndmask_b32_e64 v34, v34, v28, s[6:7]
	v_and_b32_e32 v28, 0xffff0000, v31
	v_mov_b32_e32 v31, v53
	v_and_b32_e32 v29, 0xffff0000, v35
	v_sub_f32_e32 v29, v29, v28
	v_fmac_f32_e32 v28, v29, v31
	v_mul_f32_e32 v31, v54, v28
	v_exp_f32_e32 v31, v31
	s_nop 0
	v_add_f32_e32 v31, 1.0, v31
	v_rcp_f32_e32 v31, v31
	s_nop 0
	v_fma_f32 v31, v31, v55, v56
	v_cndmask_b32_e64 v31, v31, v28, s[6:7]
	v_lshl_add_u64 v[28:29], s[16:17], 0, v[2:3]
	v_cvt_pk_bf16_f32 v44, v44, v30
	v_cvt_pk_bf16_f32 v45, v34, v31
	v_lshlrev_b64 v[30:31], 9, v[36:37]
	v_cvt_pk_bf16_f32 v42, v42, v32
	v_cvt_pk_bf16_f32 v43, v43, v33
	v_lshl_add_u64 v[30:31], v[28:29], 0, v[30:31]
	global_store_dwordx4 v[30:31], v[42:45], off
	s_and_saveexec_b64 s[22:23], s[12:13]
	s_cbranch_execz .LBB0_203
	v_mov_b32_e32 v31, v46
	v_lshlrev_b32_e32 v30, 16, v24
	v_lshlrev_b32_e32 v2, 16, v20
	v_sub_f32_e32 v2, v2, v30
	v_fmac_f32_e32 v30, v2, v31
	v_mul_f32_e32 v2, v54, v30
	v_exp_f32_e32 v2, v2
	s_nop 0
	v_add_f32_e32 v2, 1.0, v2
	v_rcp_f32_e32 v2, v2
	s_nop 0
	v_fma_f32 v2, v2, v55, v56
	v_cndmask_b32_e64 v2, v2, v30, s[6:7]
	v_mov_b32_e32 v30, v47
	v_and_b32_e32 v24, 0xffff0000, v24
	v_and_b32_e32 v20, 0xffff0000, v20
	v_sub_f32_e32 v20, v20, v24
	v_fmac_f32_e32 v24, v20, v30
	v_mul_f32_e32 v20, v54, v24
	v_exp_f32_e32 v20, v20
	s_nop 0
	v_add_f32_e32 v20, 1.0, v20
	v_rcp_f32_e32 v20, v20
	s_nop 0
	v_fma_f32 v20, v20, v55, v56
	v_cndmask_b32_e64 v20, v20, v24, s[6:7]
	v_mov_b32_e32 v31, v48
	v_lshlrev_b32_e32 v30, 16, v25
	v_lshlrev_b32_e32 v24, 16, v21
	v_sub_f32_e32 v24, v24, v30
	v_fmac_f32_e32 v30, v24, v31
	v_mul_f32_e32 v24, v54, v30
	v_exp_f32_e32 v24, v24
	s_nop 0
	v_add_f32_e32 v24, 1.0, v24
	v_rcp_f32_e32 v24, v24
	s_nop 0
	v_fma_f32 v24, v24, v55, v56
	v_cndmask_b32_e64 v24, v24, v30, s[6:7]
	v_mov_b32_e32 v30, v49
	v_and_b32_e32 v25, 0xffff0000, v25
	v_and_b32_e32 v21, 0xffff0000, v21
	v_sub_f32_e32 v21, v21, v25
	v_fmac_f32_e32 v25, v21, v30
	v_mul_f32_e32 v21, v54, v25
	v_exp_f32_e32 v21, v21
	s_nop 0
	v_add_f32_e32 v21, 1.0, v21
	v_rcp_f32_e32 v21, v21
	s_nop 0
	v_fma_f32 v21, v21, v55, v56
	v_cndmask_b32_e64 v21, v21, v25, s[6:7]
	v_mov_b32_e32 v31, v50
	v_lshlrev_b32_e32 v30, 16, v26
	v_lshlrev_b32_e32 v25, 16, v22
	v_sub_f32_e32 v25, v25, v30
	v_fmac_f32_e32 v30, v25, v31
	v_mul_f32_e32 v25, v54, v30
	v_exp_f32_e32 v25, v25
	s_nop 0
	v_add_f32_e32 v25, 1.0, v25
	v_rcp_f32_e32 v25, v25
	s_nop 0
	v_fma_f32 v25, v25, v55, v56
	v_cndmask_b32_e64 v25, v25, v30, s[6:7]
	v_mov_b32_e32 v30, v51
	v_and_b32_e32 v26, 0xffff0000, v26
	v_and_b32_e32 v22, 0xffff0000, v22
	v_sub_f32_e32 v22, v22, v26
	v_fmac_f32_e32 v26, v22, v30
	v_mul_f32_e32 v22, v54, v26
	v_exp_f32_e32 v22, v22
	s_nop 0
	v_add_f32_e32 v22, 1.0, v22
	v_rcp_f32_e32 v22, v22
	s_nop 0
	v_fma_f32 v22, v22, v55, v56
	v_cndmask_b32_e64 v22, v22, v26, s[6:7]
	v_mov_b32_e32 v31, v52
	v_lshlrev_b32_e32 v30, 16, v27
	v_lshlrev_b32_e32 v26, 16, v23
	v_sub_f32_e32 v26, v26, v30
	v_fmac_f32_e32 v30, v26, v31
	v_mul_f32_e32 v26, v54, v30
	v_exp_f32_e32 v26, v26
	s_nop 0
	v_add_f32_e32 v26, 1.0, v26
	v_rcp_f32_e32 v26, v26
	s_nop 0
	v_fma_f32 v26, v26, v55, v56
	v_cndmask_b32_e64 v26, v26, v30, s[6:7]
	v_mov_b32_e32 v30, v53
	v_and_b32_e32 v27, 0xffff0000, v27
	v_and_b32_e32 v23, 0xffff0000, v23
	v_sub_f32_e32 v23, v23, v27
	v_fmac_f32_e32 v27, v23, v30
	v_mul_f32_e32 v23, v54, v27
	v_exp_f32_e32 v23, v23
	s_nop 0
	v_add_f32_e32 v23, 1.0, v23
	v_rcp_f32_e32 v23, v23
	s_nop 0
	v_fma_f32 v23, v23, v55, v56
	v_cndmask_b32_e64 v23, v23, v27, s[6:7]
	v_ashrrev_i32_e32 v30, 5, v39
	v_ashrrev_i32_e32 v31, 31, v30
	v_cvt_pk_bf16_f32 v21, v24, v21
	v_cvt_pk_bf16_f32 v22, v25, v22
	v_lshlrev_b64 v[24:25], 9, v[30:31]
	v_cvt_pk_bf16_f32 v20, v2, v20
	v_cvt_pk_bf16_f32 v23, v26, v23
	v_lshl_add_u64 v[24:25], v[28:29], 0, v[24:25]
	global_store_dwordx4 v[24:25], v[20:23], off
	s_and_b64 exec, exec, s[10:11]
	s_cbranch_execz .LBB0_203
; __device__ __forceinline__ float fast_sigmoid(float x) { return __builtin_amdgcn_rcpf(1.0f + __builtin_amdgcn_exp2f(-1.4426950408889634f * x)); }
; __device__ __forceinline__ void unpack8(const u32x4 w, float (&f)[8]) { f[0] = bflo(w.x); f[1] = bfhi(w.x); f[2] = bflo(w.y); f[3] = bfhi(w.y); f[4] = bflo(w.z); f[5] = bfhi(w.z); f[6] = bflo(w.w); f[7] = bfhi(w.w); }
; __device__ __forceinline__ u32x4 pack8(const float (&f)[8]) { return (u32x4){pk2(f[0], f[1]), pk2(f[2], f[3]), pk2(f[4], f[5]), pk2(f[6], f[7])}; }
; __device__ __forceinline__ void el_phase(const KAS Args& a, int i, const int tid_, const int bid, const int nblk) {
;     ...
;         for (int k = 0; k < 4; ++k) { const int idx = ib + k * NGT; if (idx >= M * 32) break; const int m = idx >> 5, c0 = (idx & 31) * 8;
;             float zc[8], zp[8], o[8]; unpack8(rc[k], zc); unpack8(rp[k], zp);
; #pragma unroll
;             for (int e = 0; e < 8; ++e) { const float z = zc[e] + (zp[e] - zc[e]) * mu[c0 + e];
;                 o[e] = (c0 < 64) ? (2.0f * fast_sigmoid(2.0f * z) - 1.0f) : (c0 < 128 ? z : fast_sigmoid(z)); }
;             *(u32x4*)(LA + (size_t)m * LAC + c0) = pack8(o); } }
	v_mov_b32_e32 v21, v46
	v_lshlrev_b32_e32 v20, 16, v12
	v_lshlrev_b32_e32 v2, 16, v16
	v_sub_f32_e32 v2, v2, v20
	v_fmac_f32_e32 v20, v2, v21
	v_mul_f32_e32 v2, v54, v20
	v_exp_f32_e32 v2, v2
	s_nop 0
	v_add_f32_e32 v2, 1.0, v2
	v_rcp_f32_e32 v2, v2
	s_nop 0
	v_fma_f32 v2, v2, v55, v56
	v_cndmask_b32_e64 v2, v2, v20, s[6:7]
	v_and_b32_e32 v20, 0xffff0000, v12
	v_and_b32_e32 v12, 0xffff0000, v16
	v_mov_b32_e32 v16, v47
	v_sub_f32_e32 v12, v12, v20
	v_fmac_f32_e32 v20, v12, v16
	v_mul_f32_e32 v12, v54, v20
	v_exp_f32_e32 v12, v12
	s_nop 0
	v_add_f32_e32 v12, 1.0, v12
	v_rcp_f32_e32 v12, v12
	s_nop 0
	v_fma_f32 v12, v12, v55, v56
	v_cndmask_b32_e64 v12, v12, v20, s[6:7]
	v_mov_b32_e32 v21, v48
	v_lshlrev_b32_e32 v20, 16, v13
	v_lshlrev_b32_e32 v16, 16, v17
	v_sub_f32_e32 v16, v16, v20
	v_fmac_f32_e32 v20, v16, v21
	v_mul_f32_e32 v16, v54, v20
	v_exp_f32_e32 v16, v16
	s_nop 0
	v_add_f32_e32 v16, 1.0, v16
	v_rcp_f32_e32 v16, v16
	s_nop 0
	v_fma_f32 v16, v16, v55, v56
	v_cndmask_b32_e64 v16, v16, v20, s[6:7]
	v_and_b32_e32 v20, 0xffff0000, v13
	v_and_b32_e32 v13, 0xffff0000, v17
	v_mov_b32_e32 v17, v49
	v_sub_f32_e32 v13, v13, v20
	v_fmac_f32_e32 v20, v13, v17
	v_mul_f32_e32 v13, v54, v20
	v_exp_f32_e32 v13, v13
	s_nop 0
	v_add_f32_e32 v13, 1.0, v13
	v_rcp_f32_e32 v13, v13
	s_nop 0
	v_fma_f32 v13, v13, v55, v56
	v_cndmask_b32_e64 v13, v13, v20, s[6:7]
	v_mov_b32_e32 v21, v50
	v_lshlrev_b32_e32 v20, 16, v14
	v_lshlrev_b32_e32 v17, 16, v18
	v_sub_f32_e32 v17, v17, v20
	v_fmac_f32_e32 v20, v17, v21
	v_mul_f32_e32 v17, v54, v20
	v_exp_f32_e32 v17, v17
	s_nop 0
	v_add_f32_e32 v17, 1.0, v17
	v_rcp_f32_e32 v17, v17
	s_nop 0
	v_fma_f32 v17, v17, v55, v56
	v_cndmask_b32_e64 v17, v17, v20, s[6:7]
	v_and_b32_e32 v20, 0xffff0000, v14
	v_and_b32_e32 v14, 0xffff0000, v18
	v_mov_b32_e32 v18, v51
	v_sub_f32_e32 v14, v14, v20
	v_fmac_f32_e32 v20, v14, v18
	v_mul_f32_e32 v14, v54, v20
	v_exp_f32_e32 v14, v14
	s_nop 0
	v_add_f32_e32 v14, 1.0, v14
	v_rcp_f32_e32 v14, v14
	s_nop 0
	v_fma_f32 v14, v14, v55, v56
	v_cndmask_b32_e64 v14, v14, v20, s[6:7]
	v_mov_b32_e32 v21, v52
	v_lshlrev_b32_e32 v20, 16, v15
	v_lshlrev_b32_e32 v18, 16, v19
	v_sub_f32_e32 v18, v18, v20
	v_fmac_f32_e32 v20, v18, v21
	v_mul_f32_e32 v18, v54, v20
	v_exp_f32_e32 v18, v18
	s_nop 0
	v_add_f32_e32 v18, 1.0, v18
	v_rcp_f32_e32 v18, v18
	s_nop 0
	v_fma_f32 v18, v18, v55, v56
	v_cndmask_b32_e64 v18, v18, v20, s[6:7]
	v_mov_b32_e32 v20, v53
	v_and_b32_e32 v15, 0xffff0000, v15
	v_and_b32_e32 v19, 0xffff0000, v19
	v_sub_f32_e32 v19, v19, v15
	v_fmac_f32_e32 v15, v19, v20
	v_mul_f32_e32 v19, v54, v15
	v_exp_f32_e32 v19, v19
	s_nop 0
	v_add_f32_e32 v19, 1.0, v19
	v_rcp_f32_e32 v19, v19
	s_nop 0
	v_fma_f32 v19, v19, v55, v56
	v_cndmask_b32_e64 v19, v19, v15, s[6:7]
	v_ashrrev_i32_e32 v20, 5, v41
	v_ashrrev_i32_e32 v21, 31, v20
	v_cvt_pk_bf16_f32 v13, v16, v13
	v_cvt_pk_bf16_f32 v14, v17, v14
	v_lshlrev_b64 v[16:17], 9, v[20:21]
	v_cvt_pk_bf16_f32 v12, v2, v12
	v_cvt_pk_bf16_f32 v15, v18, v19
	v_lshl_add_u64 v[16:17], v[28:29], 0, v[16:17]
	global_store_dwordx4 v[16:17], v[12:15], off
	s_and_b64 exec, exec, s[8:9]
	s_cbranch_execz .LBB0_203
	v_mov_b32_e32 v13, v46
	v_lshlrev_b32_e32 v12, 16, v8
	v_lshlrev_b32_e32 v2, 16, v4
	v_sub_f32_e32 v2, v2, v12
	v_fmac_f32_e32 v12, v2, v13
	v_mul_f32_e32 v2, v54, v12
	v_exp_f32_e32 v2, v2
	s_nop 0
	v_add_f32_e32 v2, 1.0, v2
	v_rcp_f32_e32 v2, v2
	s_nop 0
	v_fma_f32 v2, v2, v55, v56
	v_cndmask_b32_e64 v2, v2, v12, s[6:7]
	v_mov_b32_e32 v12, v47
	v_and_b32_e32 v8, 0xffff0000, v8
	v_and_b32_e32 v4, 0xffff0000, v4
	v_sub_f32_e32 v4, v4, v8
	v_fmac_f32_e32 v8, v4, v12
	v_mul_f32_e32 v4, v54, v8
	v_exp_f32_e32 v4, v4
	s_nop 0
	v_add_f32_e32 v4, 1.0, v4
	v_rcp_f32_e32 v4, v4
	s_nop 0
	v_fma_f32 v4, v4, v55, v56
	v_cndmask_b32_e64 v4, v4, v8, s[6:7]
	v_mov_b32_e32 v13, v48
	v_lshlrev_b32_e32 v12, 16, v9
	v_lshlrev_b32_e32 v8, 16, v5
	v_sub_f32_e32 v8, v8, v12
	v_fmac_f32_e32 v12, v8, v13
	v_mul_f32_e32 v8, v54, v12
	v_exp_f32_e32 v8, v8
	s_nop 0
	v_add_f32_e32 v8, 1.0, v8
	v_rcp_f32_e32 v8, v8
	s_nop 0
	v_fma_f32 v8, v8, v55, v56
	v_cndmask_b32_e64 v8, v8, v12, s[6:7]
	v_mov_b32_e32 v12, v49
	v_and_b32_e32 v9, 0xffff0000, v9
	v_and_b32_e32 v5, 0xffff0000, v5
	v_sub_f32_e32 v5, v5, v9
	v_fmac_f32_e32 v9, v5, v12
	v_mul_f32_e32 v5, v54, v9
	v_exp_f32_e32 v5, v5
	s_nop 0
	v_add_f32_e32 v5, 1.0, v5
	v_rcp_f32_e32 v5, v5
	s_nop 0
	v_fma_f32 v5, v5, v55, v56
	v_cndmask_b32_e64 v5, v5, v9, s[6:7]
	v_mov_b32_e32 v13, v50
	v_lshlrev_b32_e32 v12, 16, v10
	v_lshlrev_b32_e32 v9, 16, v6
	v_sub_f32_e32 v9, v9, v12
	v_fmac_f32_e32 v12, v9, v13
	v_mul_f32_e32 v9, v54, v12
	v_exp_f32_e32 v9, v9
	s_nop 0
	v_add_f32_e32 v9, 1.0, v9
	v_rcp_f32_e32 v9, v9
	s_nop 0
	v_fma_f32 v9, v9, v55, v56
	v_cndmask_b32_e64 v9, v9, v12, s[6:7]
	v_mov_b32_e32 v12, v51
	v_and_b32_e32 v10, 0xffff0000, v10
	v_and_b32_e32 v6, 0xffff0000, v6
	v_sub_f32_e32 v6, v6, v10
	v_fmac_f32_e32 v10, v6, v12
	v_mul_f32_e32 v6, v54, v10
	v_exp_f32_e32 v6, v6
	s_nop 0
	v_add_f32_e32 v6, 1.0, v6
	v_rcp_f32_e32 v6, v6
	s_nop 0
	v_fma_f32 v6, v6, v55, v56
	v_cndmask_b32_e64 v6, v6, v10, s[6:7]
	v_mov_b32_e32 v13, v52
	v_lshlrev_b32_e32 v12, 16, v11
	v_lshlrev_b32_e32 v10, 16, v7
	v_sub_f32_e32 v10, v10, v12
	v_fmac_f32_e32 v12, v10, v13
	v_mul_f32_e32 v10, v54, v12
	v_exp_f32_e32 v10, v10
	s_nop 0
	v_add_f32_e32 v10, 1.0, v10
	v_rcp_f32_e32 v10, v10
	s_nop 0
	v_fma_f32 v10, v10, v55, v56
	v_cndmask_b32_e64 v10, v10, v12, s[6:7]
	v_mov_b32_e32 v1, v53
	v_and_b32_e32 v0, 0xffff0000, v11
	v_and_b32_e32 v7, 0xffff0000, v7
	v_sub_f32_e32 v7, v7, v0
	v_fmac_f32_e32 v0, v7, v1
	v_mul_f32_e32 v1, v54, v0
	v_exp_f32_e32 v1, v1
	s_nop 0
	v_add_f32_e32 v1, 1.0, v1
	v_rcp_f32_e32 v1, v1
	s_nop 0
	v_fma_f32 v1, v1, v55, v56
	v_cndmask_b32_e64 v1, v1, v0, s[6:7]
	s_branch .LBB0_202
